# speedup vs baseline: 1.0027x; 1.0027x over previous
.LBB0_376:
	s_waitcnt lgkmcnt(8)
	ds_read_b64_tr_b16 v[140:141], v215 offset:1024
	ds_read_b64_tr_b16 v[142:143], v215 offset:5120
	ds_read_b64_tr_b16 v[144:145], v215 offset:9216
	ds_read_b64_tr_b16 v[146:147], v215 offset:13312
	v_mfma_f32_16x16x32_bf16 v[60:63], v[120:123], v[168:171], v[60:63]
	v_max_i32_e32 v240, v84, v85
	v_max3_i32 v241, v87, v96, v97
	v_max3_i32 v240, v240, v86, v98
	v_max3_i32 v241, v241, v100, v101
	v_mfma_f32_16x16x32_bf16 v[64:67], v[124:127], v[168:171], v[64:67]
	v_max3_i32 v240, v240, v99, v102
	v_max3_i32 v241, v241, v108, v109
	v_max3_i32 v240, v240, v103, v110
	v_max3_i32 v242, v240, v111, v241
	v_mfma_f32_16x16x32_bf16 v[60:63], v[112:115], v[172:175], v[60:63]
	v_max_i32_e32 v240, v80, v81
	v_max3_i32 v241, v83, v88, v89
	v_max3_i32 v240, v240, v82, v90
	v_max3_i32 v241, v241, v92, v93
	v_mfma_f32_16x16x32_bf16 v[64:67], v[116:119], v[172:175], v[64:67]
	v_max3_i32 v240, v240, v91, v94
	v_max3_i32 v241, v241, v104, v105
	v_max3_i32 v240, v240, v95, v106
	v_max3_i32 v241, v240, v107, v241
	v_max_f32_e32 v240, v241, v241
	v_max_f32_e32 v243, v242, v242
	v_max_f32_e32 v212, v243, v240
	v_cmp_ge_f32_e32 vcc, s3, v212
	s_cmp_lg_u64 vcc, exec
	s_cselect_b64 s[6:7], -1, 0
	s_cbranch_scc1 .LBB0_388
	v_mov_b32_e32 v249, 1.0
	v_mov_b32_e32 v248, 1.0
.LBB0_390:
	s_waitcnt lgkmcnt(8)
	ds_read_b64_tr_b16 v[160:161], v214 offset:2048
	ds_read_b64_tr_b16 v[162:163], v214 offset:6144
	ds_read_b64_tr_b16 v[164:165], v214 offset:10240
	ds_read_b64_tr_b16 v[166:167], v214 offset:14336
	v_mfma_f32_16x16x32_bf16 v[52:55], v[120:123], v[176:179], v[52:55]
	v_exp_f32_e32 v241, v84
	v_mfma_f32_16x16x32_bf16 v[48:51], v[124:127], v[176:179], v[48:51]
	v_exp_f32_e32 v244, v85
	v_mfma_f32_16x16x32_bf16 v[52:55], v[112:115], v[180:183], v[52:55]
	v_exp_f32_e32 v245, v86
	v_mfma_f32_16x16x32_bf16 v[48:51], v[116:119], v[180:183], v[48:51]
	v_exp_f32_e32 v247, v87
	v_exp_f32_e32 v240, v96
	s_waitcnt lgkmcnt(8)
	ds_read_b64_tr_b16 v[168:169], v215 offset:2048
	ds_read_b64_tr_b16 v[170:171], v215 offset:6144
	ds_read_b64_tr_b16 v[172:173], v215 offset:10240
	ds_read_b64_tr_b16 v[174:175], v215 offset:14336
	v_mfma_f32_16x16x32_bf16 v[44:47], v[120:123], v[184:187], v[44:47]
	v_exp_f32_e32 v242, v97
	v_mfma_f32_16x16x32_bf16 v[40:43], v[124:127], v[184:187], v[40:43]
	v_exp_f32_e32 v243, v98
	v_mfma_f32_16x16x32_bf16 v[44:47], v[112:115], v[188:191], v[44:47]
	v_exp_f32_e32 v246, v99
	v_mfma_f32_16x16x32_bf16 v[40:43], v[116:119], v[188:191], v[40:43]
	v_exp_f32_e32 v137, v80
	v_exp_f32_e32 v148, v81
	s_waitcnt lgkmcnt(8)
	ds_read_b64_tr_b16 v[176:177], v214 offset:3072
	ds_read_b64_tr_b16 v[178:179], v214 offset:7168
	ds_read_b64_tr_b16 v[180:181], v214 offset:11264
	ds_read_b64_tr_b16 v[182:183], v214 offset:15360
	v_mfma_f32_16x16x32_bf16 v[32:35], v[120:123], v[140:143], v[32:35]
	v_exp_f32_e32 v149, v82
	v_mfma_f32_16x16x32_bf16 v[36:39], v[124:127], v[140:143], v[36:39]
	v_exp_f32_e32 v151, v83
	v_mfma_f32_16x16x32_bf16 v[32:35], v[112:115], v[144:147], v[32:35]
	v_exp_f32_e32 v136, v89
	v_mfma_f32_16x16x32_bf16 v[36:39], v[116:119], v[144:147], v[36:39]
	v_exp_f32_e32 v139, v90
	v_exp_f32_e32 v150, v91
	s_waitcnt lgkmcnt(8)
	ds_read_b64_tr_b16 v[184:185], v215 offset:3072
	ds_read_b64_tr_b16 v[186:187], v215 offset:7168
	ds_read_b64_tr_b16 v[188:189], v215 offset:11264
	ds_read_b64_tr_b16 v[190:191], v215 offset:15360
	v_mfma_f32_16x16x32_bf16 v[20:23], v[120:123], v[160:163], v[20:23]
	v_exp_f32_e32 v129, v92
	v_mfma_f32_16x16x32_bf16 v[16:19], v[124:127], v[160:163], v[16:19]
	v_exp_f32_e32 v138, v95
	v_mfma_f32_16x16x32_bf16 v[20:23], v[112:115], v[164:167], v[20:23]
	v_exp_f32_e32 v128, v104
	v_mfma_f32_16x16x32_bf16 v[16:19], v[116:119], v[164:167], v[16:19]
	v_exp_f32_e32 v130, v105
	v_exp_f32_e32 v131, v106
	s_waitcnt lgkmcnt(8)
	v_mfma_f32_16x16x32_bf16 v[28:31], v[120:123], v[168:171], v[28:31]
	v_exp_f32_e32 v153, v100
	v_mfma_f32_16x16x32_bf16 v[24:27], v[124:127], v[168:171], v[24:27]
	v_exp_f32_e32 v152, v108
	v_mfma_f32_16x16x32_bf16 v[28:31], v[112:115], v[172:175], v[28:31]
	v_exp_f32_e32 v154, v109
	v_mfma_f32_16x16x32_bf16 v[24:27], v[116:119], v[172:175], v[24:27]
	v_exp_f32_e32 v155, v110
	s_waitcnt lgkmcnt(4)
	v_mfma_f32_16x16x32_bf16 v[12:15], v[120:123], v[176:179], v[12:15]
	v_exp_f32_e32 v156, v101
	v_mfma_f32_16x16x32_bf16 v[8:11], v[124:127], v[176:179], v[8:11]
	v_exp_f32_e32 v158, v102
	v_mfma_f32_16x16x32_bf16 v[12:15], v[112:115], v[180:183], v[12:15]
	v_exp_f32_e32 v159, v103
	v_mfma_f32_16x16x32_bf16 v[8:11], v[116:119], v[180:183], v[8:11]
	v_exp_f32_e32 v157, v111
	s_waitcnt lgkmcnt(0)
	v_mfma_f32_16x16x32_bf16 v[4:7], v[120:123], v[184:187], v[4:7]
	v_exp_f32_e32 v132, v88
	v_mfma_f32_16x16x32_bf16 v[0:3], v[124:127], v[184:187], v[0:3]
	v_exp_f32_e32 v134, v93
	v_mfma_f32_16x16x32_bf16 v[4:7], v[112:115], v[188:191], v[4:7]
	v_exp_f32_e32 v135, v94
	v_mfma_f32_16x16x32_bf16 v[0:3], v[116:119], v[188:191], v[0:3]
	v_exp_f32_e32 v133, v107
	s_waitcnt vmcnt(3)
	s_waitcnt lgkmcnt(0)
	s_add_i32 s19, s19, 0x8000
	s_addk_i32 s20, 0x4000
	s_cmp_ge_i32 s21, s14
	s_cselect_b64 s[0:1], -1, 0
	s_and_b64 vcc, exec, s[0:1]
	s_mov_b32 s23, s21
	s_barrier
	s_cbranch_vccz .LBB0_369
	s_branch .LBB0_392

; DEV void diff16_pass(const bf16_t* __restrict__ proj, int qcol, int kcol, int vcol, int q0, f32x4 (&o)[2][8], f32x4 (&l_out)[2], unsigned char* lds) {
;     ...
;   f32x4 ol[2] = {(f32x4){0.f, 0.f, 0.f, 0.f}, (f32x4){0.f, 0.f, 0.f, 0.f}};
;   const bf16x8 ones = {0x3F80, 0x3F80, 0x3F80, 0x3F80, 0x3F80, 0x3F80, 0x3F80, 0x3F80};
;   f32x4 negm[2] = {(f32x4){0.f, 0.f, 0.f, 0.f}, (f32x4){0.f, 0.f, 0.f, 0.f}};
; #pragma unroll
;   for (int g = 0; g < 2; ++g)
; #pragma unroll
;     for (int cb = 0; cb < 8; ++cb) o[g][cb] = (f32x4){0.f, 0.f, 0.f, 0.f};
.LBB0_388:
	v_mov_b32_e32 v249, 1.0
	s_branch .LBB0_378
.LBB0_391:
	s_mov_b32 s76, s77
	s_mov_b32 s78, s77
	s_mov_b32 s79, s77
	v_mov_b64_e32 v[56:57], s[76:77]
	v_mov_b64_e32 v[68:69], s[76:77]
	v_mov_b64_e32 v[60:61], s[76:77]
	v_mov_b64_e32 v[52:53], s[76:77]
	v_mov_b64_e32 v[44:45], s[76:77]
	s_waitcnt lgkmcnt(0)
	v_mov_b64_e32 v[32:33], s[76:77]
	v_mov_b64_e32 v[20:21], s[76:77]
	v_mov_b64_e32 v[28:29], s[76:77]
	v_mov_b64_e32 v[12:13], s[76:77]
	v_mov_b64_e32 v[4:5], s[76:77]
	v_mov_b64_e32 v[64:65], s[76:77]
	v_mov_b64_e32 v[48:49], s[76:77]
	v_mov_b64_e32 v[40:41], s[76:77]
	v_mov_b64_e32 v[36:37], s[76:77]
	v_mov_b64_e32 v[16:17], s[76:77]
	v_mov_b64_e32 v[24:25], s[76:77]
	v_mov_b64_e32 v[8:9], s[76:77]
	v_mov_b64_e32 v[0:1], s[76:77]
	s_mov_b64 s[12:13], 0
	v_mov_b64_e32 v[58:59], s[78:79]
	v_mov_b64_e32 v[70:71], s[78:79]
	v_mov_b64_e32 v[62:63], s[78:79]
	v_mov_b64_e32 v[54:55], s[78:79]
	v_mov_b64_e32 v[46:47], s[78:79]
	v_mov_b64_e32 v[34:35], s[78:79]
	v_mov_b64_e32 v[22:23], s[78:79]
	v_mov_b64_e32 v[30:31], s[78:79]
	v_mov_b64_e32 v[14:15], s[78:79]
	v_mov_b64_e32 v[6:7], s[78:79]
	v_mov_b64_e32 v[66:67], s[78:79]
	v_mov_b64_e32 v[50:51], s[78:79]
	v_mov_b64_e32 v[42:43], s[78:79]
	v_mov_b64_e32 v[38:39], s[78:79]
	v_mov_b64_e32 v[18:19], s[78:79]
	v_mov_b64_e32 v[26:27], s[78:79]
	v_mov_b64_e32 v[10:11], s[78:79]
	v_mov_b64_e32 v[2:3], s[78:79]

.LBB0_403:
	s_waitcnt lgkmcnt(8)
	ds_read_b64_tr_b16 v[140:141], v215 offset:1024
	ds_read_b64_tr_b16 v[142:143], v215 offset:5120
	ds_read_b64_tr_b16 v[144:145], v215 offset:9216
	ds_read_b64_tr_b16 v[146:147], v215 offset:13312
	v_mfma_f32_16x16x32_bf16 v[60:63], v[120:123], v[168:171], v[60:63]
	v_max_i32_e32 v212, v84, v85
	v_max3_i32 v213, v87, v96, v97
	v_max3_i32 v212, v212, v86, v98
	v_max3_i32 v213, v213, v100, v101
	v_mfma_f32_16x16x32_bf16 v[64:67], v[124:127], v[168:171], v[64:67]
	v_max3_i32 v212, v212, v99, v102
	v_max3_i32 v213, v213, v108, v109
	v_max3_i32 v212, v212, v103, v110
	v_max3_i32 v242, v212, v111, v213
	v_mfma_f32_16x16x32_bf16 v[60:63], v[112:115], v[172:175], v[60:63]
	v_max_i32_e32 v212, v80, v81
	v_max3_i32 v213, v83, v88, v89
	v_max3_i32 v212, v212, v82, v90
	v_max3_i32 v213, v213, v92, v93
	v_mfma_f32_16x16x32_bf16 v[64:67], v[116:119], v[172:175], v[64:67]
	v_max3_i32 v212, v212, v91, v94
	v_max3_i32 v213, v213, v104, v105
	v_max3_i32 v212, v212, v95, v106
	v_max3_i32 v241, v212, v107, v213
	v_max_f32_e32 v240, v241, v241
	v_max_f32_e32 v243, v242, v242
	v_max_f32_e32 v212, v243, v240
	v_cmp_ge_f32_e32 vcc, s3, v212
	s_cmp_lg_u64 vcc, exec
	s_cselect_b64 s[6:7], -1, 0
	s_cbranch_scc1 .LBB0_415
	v_mov_b32_e32 v249, 1.0
	v_mov_b32_e32 v248, 1.0
.LBB0_417:
	s_waitcnt lgkmcnt(8)
	ds_read_b64_tr_b16 v[160:161], v214 offset:2048
	ds_read_b64_tr_b16 v[162:163], v214 offset:6144
	ds_read_b64_tr_b16 v[164:165], v214 offset:10240
	ds_read_b64_tr_b16 v[166:167], v214 offset:14336
	v_mfma_f32_16x16x32_bf16 v[52:55], v[120:123], v[176:179], v[52:55]
	v_exp_f32_e32 v241, v84
	v_mfma_f32_16x16x32_bf16 v[48:51], v[124:127], v[176:179], v[48:51]
	v_exp_f32_e32 v244, v85
	v_mfma_f32_16x16x32_bf16 v[52:55], v[112:115], v[180:183], v[52:55]
	v_exp_f32_e32 v245, v86
	v_mfma_f32_16x16x32_bf16 v[48:51], v[116:119], v[180:183], v[48:51]
	v_exp_f32_e32 v247, v87
	v_exp_f32_e32 v240, v96
	s_waitcnt lgkmcnt(8)
	ds_read_b64_tr_b16 v[168:169], v215 offset:2048
	ds_read_b64_tr_b16 v[170:171], v215 offset:6144
	ds_read_b64_tr_b16 v[172:173], v215 offset:10240
	ds_read_b64_tr_b16 v[174:175], v215 offset:14336
	v_mfma_f32_16x16x32_bf16 v[44:47], v[120:123], v[184:187], v[44:47]
	v_exp_f32_e32 v242, v97
	v_mfma_f32_16x16x32_bf16 v[40:43], v[124:127], v[184:187], v[40:43]
	v_exp_f32_e32 v243, v98
	v_mfma_f32_16x16x32_bf16 v[44:47], v[112:115], v[188:191], v[44:47]
	v_exp_f32_e32 v246, v99
	v_mfma_f32_16x16x32_bf16 v[40:43], v[116:119], v[188:191], v[40:43]
	v_exp_f32_e32 v137, v80
	v_exp_f32_e32 v148, v81
	s_waitcnt lgkmcnt(8)
	ds_read_b64_tr_b16 v[176:177], v214 offset:3072
	ds_read_b64_tr_b16 v[178:179], v214 offset:7168
	ds_read_b64_tr_b16 v[180:181], v214 offset:11264
	ds_read_b64_tr_b16 v[182:183], v214 offset:15360
	v_mfma_f32_16x16x32_bf16 v[32:35], v[120:123], v[140:143], v[32:35]
	v_exp_f32_e32 v149, v82
	v_mfma_f32_16x16x32_bf16 v[36:39], v[124:127], v[140:143], v[36:39]
	v_exp_f32_e32 v151, v83
	v_mfma_f32_16x16x32_bf16 v[32:35], v[112:115], v[144:147], v[32:35]
	v_exp_f32_e32 v136, v89
	v_mfma_f32_16x16x32_bf16 v[36:39], v[116:119], v[144:147], v[36:39]
	v_exp_f32_e32 v139, v90
	v_exp_f32_e32 v150, v91
	s_waitcnt lgkmcnt(8)
	ds_read_b64_tr_b16 v[184:185], v215 offset:3072
	ds_read_b64_tr_b16 v[186:187], v215 offset:7168
	ds_read_b64_tr_b16 v[188:189], v215 offset:11264
	ds_read_b64_tr_b16 v[190:191], v215 offset:15360
	v_mfma_f32_16x16x32_bf16 v[20:23], v[120:123], v[160:163], v[20:23]
	v_exp_f32_e32 v129, v92
	v_mfma_f32_16x16x32_bf16 v[16:19], v[124:127], v[160:163], v[16:19]
	v_exp_f32_e32 v138, v95
	v_mfma_f32_16x16x32_bf16 v[20:23], v[112:115], v[164:167], v[20:23]
	v_exp_f32_e32 v128, v104
	v_mfma_f32_16x16x32_bf16 v[16:19], v[116:119], v[164:167], v[16:19]
	v_exp_f32_e32 v130, v105
	v_exp_f32_e32 v131, v106
	s_waitcnt lgkmcnt(8)
	v_mfma_f32_16x16x32_bf16 v[28:31], v[120:123], v[168:171], v[28:31]
	v_exp_f32_e32 v153, v100
	v_mfma_f32_16x16x32_bf16 v[24:27], v[124:127], v[168:171], v[24:27]
	v_exp_f32_e32 v152, v108
	v_mfma_f32_16x16x32_bf16 v[28:31], v[112:115], v[172:175], v[28:31]
	v_exp_f32_e32 v154, v109
	v_mfma_f32_16x16x32_bf16 v[24:27], v[116:119], v[172:175], v[24:27]
	v_exp_f32_e32 v155, v110
	s_waitcnt lgkmcnt(4)
	v_mfma_f32_16x16x32_bf16 v[12:15], v[120:123], v[176:179], v[12:15]
	v_exp_f32_e32 v156, v101
	v_mfma_f32_16x16x32_bf16 v[8:11], v[124:127], v[176:179], v[8:11]
	v_exp_f32_e32 v158, v102
	v_mfma_f32_16x16x32_bf16 v[12:15], v[112:115], v[180:183], v[12:15]
	v_exp_f32_e32 v159, v103
	v_mfma_f32_16x16x32_bf16 v[8:11], v[116:119], v[180:183], v[8:11]
	v_exp_f32_e32 v157, v111
	s_waitcnt lgkmcnt(0)
	v_mfma_f32_16x16x32_bf16 v[4:7], v[120:123], v[184:187], v[4:7]
	v_exp_f32_e32 v132, v88
	v_mfma_f32_16x16x32_bf16 v[0:3], v[124:127], v[184:187], v[0:3]
	v_exp_f32_e32 v134, v93
	v_mfma_f32_16x16x32_bf16 v[4:7], v[112:115], v[188:191], v[4:7]
	v_exp_f32_e32 v135, v94
	v_mfma_f32_16x16x32_bf16 v[0:3], v[116:119], v[188:191], v[0:3]
	v_exp_f32_e32 v133, v107
	s_waitcnt vmcnt(3)
	s_waitcnt lgkmcnt(0)
	s_add_i32 s15, s15, 0x8000
	s_addk_i32 s16, 0x4000
	s_cmp_ge_i32 s17, s14
	s_cselect_b64 s[0:1], -1, 0
	s_and_b64 vcc, exec, s[0:1]
	s_mov_b32 s19, s17
	s_barrier
	s_cbranch_vccz .LBB0_396
	s_branch .LBB0_419

; DEV void diff16_pass(const bf16_t* __restrict__ proj, int qcol, int kcol, int vcol, int q0, f32x4 (&o)[2][8], f32x4 (&l_out)[2], unsigned char* lds) {
;     ...
;   f32x4 ol[2] = {(f32x4){0.f, 0.f, 0.f, 0.f}, (f32x4){0.f, 0.f, 0.f, 0.f}};
;   const bf16x8 ones = {0x3F80, 0x3F80, 0x3F80, 0x3F80, 0x3F80, 0x3F80, 0x3F80, 0x3F80};
;   f32x4 negm[2] = {(f32x4){0.f, 0.f, 0.f, 0.f}, (f32x4){0.f, 0.f, 0.f, 0.f}};
; #pragma unroll
;   for (int g = 0; g < 2; ++g)
; #pragma unroll
;     for (int cb = 0; cb < 8; ++cb) o[g][cb] = (f32x4){0.f, 0.f, 0.f, 0.f};
.LBB0_415:
	v_mov_b32_e32 v249, 1.0
	s_branch .LBB0_405
.LBB0_418:
	s_mov_b32 s76, s77
	s_mov_b32 s78, s77
	s_mov_b32 s79, s77
	v_mov_b64_e32 v[56:57], s[76:77]
	v_mov_b64_e32 v[68:69], s[76:77]
	v_mov_b64_e32 v[60:61], s[76:77]
	v_mov_b64_e32 v[52:53], s[76:77]
	v_mov_b64_e32 v[44:45], s[76:77]
	s_waitcnt lgkmcnt(0)
	v_mov_b64_e32 v[32:33], s[76:77]
	v_mov_b64_e32 v[20:21], s[76:77]
	v_mov_b64_e32 v[28:29], s[76:77]
	v_mov_b64_e32 v[12:13], s[76:77]
	v_mov_b64_e32 v[4:5], s[76:77]
	v_mov_b64_e32 v[64:65], s[76:77]
	v_mov_b64_e32 v[48:49], s[76:77]
	v_mov_b64_e32 v[40:41], s[76:77]
	v_mov_b64_e32 v[36:37], s[76:77]
	v_mov_b64_e32 v[16:17], s[76:77]
	v_mov_b64_e32 v[24:25], s[76:77]
	v_mov_b64_e32 v[8:9], s[76:77]
	v_mov_b64_e32 v[0:1], s[76:77]
	s_mov_b64 s[10:11], 0
	v_mov_b64_e32 v[58:59], s[78:79]
	v_mov_b64_e32 v[70:71], s[78:79]
	v_mov_b64_e32 v[62:63], s[78:79]
	v_mov_b64_e32 v[54:55], s[78:79]
	v_mov_b64_e32 v[46:47], s[78:79]
	v_mov_b64_e32 v[34:35], s[78:79]
	v_mov_b64_e32 v[22:23], s[78:79]
	v_mov_b64_e32 v[30:31], s[78:79]
	v_mov_b64_e32 v[14:15], s[78:79]
	v_mov_b64_e32 v[6:7], s[78:79]
	v_mov_b64_e32 v[66:67], s[78:79]
	v_mov_b64_e32 v[50:51], s[78:79]
	v_mov_b64_e32 v[42:43], s[78:79]
	v_mov_b64_e32 v[38:39], s[78:79]
	v_mov_b64_e32 v[18:19], s[78:79]
	v_mov_b64_e32 v[26:27], s[78:79]
	v_mov_b64_e32 v[10:11], s[78:79]
	v_mov_b64_e32 v[2:3], s[78:79]
